# phase 0b input conversion: all 12 loads of a token issued together and next token prefetched (was 24 dependent round trips per wave)
# speedup vs baseline: 1.0033x; 1.0033x over previous
.LBB0_99:
	s_or_b64 exec, exec, s[2:3]
	v_readlane_b32 s0, v247, 0
	v_ashrrev_i32_e32 v0, 6, v10
	s_lshl_b32 s0, s0, 2
	v_writelane_b32 v246, s0, 3
	v_add_u32_e32 v0, s0, v0
	s_movk_i32 s0, 0x3000
	v_cmp_gt_i32_e32 vcc, s0, v0
	s_and_saveexec_b64 s[0:1], vcc
	s_cbranch_execz .LBB0_106
	v_readfirstlane_b32 s40, v0
	v_and_b32_e32 v8, 63, v10
	v_lshlrev_b32_e32 v9, 3, v8
	v_lshlrev_b32_e32 v8, 4, v8
	v_readlane_b32 s42, v247, 1
	v_readlane_b32 s43, v247, 2
	v_readlane_b32 s44, v247, 3
	v_readlane_b32 s45, v247, 4
	v_readlane_b32 s46, v247, 51
	v_readlane_b32 s47, v247, 52
	s_lshl_b32 s41, s40, 12
	s_lshl_b32 s40, s40, 11
	s_add_u32 s58, s22, s40
	s_addc_u32 s59, s23, 0
	s_add_u32 s48, s42, s41
	s_addc_u32 s49, s43, 0
	s_add_u32 s50, s46, 0x0
	s_addc_u32 s51, s47, 0
	s_add_u32 s52, s50, 0x1000
	s_addc_u32 s53, s51, 0
	global_load_dwordx4 v[90:93], v8, s[52:53]
	global_load_dwordx4 v[106:109], v8, s[48:49]
	global_load_dwordx4 v[122:125], v8, s[50:51]
	global_load_dwordx4 v[94:97], v8, s[52:53] offset:1024
	global_load_dwordx4 v[110:113], v8, s[48:49] offset:1024
	global_load_dwordx4 v[126:129], v8, s[50:51] offset:1024
	global_load_dwordx4 v[98:101], v8, s[52:53] offset:2048
	global_load_dwordx4 v[114:117], v8, s[48:49] offset:2048
	global_load_dwordx4 v[130:133], v8, s[50:51] offset:2048
	global_load_dwordx4 v[102:105], v8, s[52:53] offset:3072
	global_load_dwordx4 v[118:121], v8, s[48:49] offset:3072
	global_load_dwordx4 v[134:137], v8, s[50:51] offset:3072
	s_add_u32 s48, s42, s41
	s_addc_u32 s49, s43, 0
	s_add_u32 s48, s48, 0x800000
	s_addc_u32 s49, s49, 0
	s_add_u32 s50, s46, 0x0
	s_addc_u32 s51, s47, 0
	s_add_u32 s52, s50, 0x1000
	s_addc_u32 s53, s51, 0
	global_load_dwordx4 v[18:21], v8, s[52:53]
	global_load_dwordx4 v[50:53], v8, s[48:49]
	global_load_dwordx4 v[66:69], v8, s[50:51]
	global_load_dwordx4 v[22:25], v8, s[52:53] offset:1024
	global_load_dwordx4 v[54:57], v8, s[48:49] offset:1024
	global_load_dwordx4 v[70:73], v8, s[50:51] offset:1024
	global_load_dwordx4 v[26:29], v8, s[52:53] offset:2048
	global_load_dwordx4 v[58:61], v8, s[48:49] offset:2048
	global_load_dwordx4 v[74:77], v8, s[50:51] offset:2048
	global_load_dwordx4 v[30:33], v8, s[52:53] offset:3072
	global_load_dwordx4 v[62:65], v8, s[48:49] offset:3072
	global_load_dwordx4 v[78:81], v8, s[50:51] offset:3072
	s_waitcnt vmcnt(21)
	v_pk_add_f32 v[90:91], v[90:91], 1.0 op_sel_hi:[1,0]
	v_pk_add_f32 v[92:93], v[92:93], 1.0 op_sel_hi:[1,0]
	v_pk_fma_f32 v[90:91], v[106:107], v[90:91], v[122:123]
	v_pk_fma_f32 v[92:93], v[108:109], v[92:93], v[124:125]
	v_cvt_pk_bf16_f32 v82, v90, v91
	v_cvt_pk_bf16_f32 v83, v92, v93
	global_store_dwordx2 v9, v[82:83], s[58:59]
	s_waitcnt vmcnt(19)
	v_pk_add_f32 v[94:95], v[94:95], 1.0 op_sel_hi:[1,0]
	v_pk_add_f32 v[96:97], v[96:97], 1.0 op_sel_hi:[1,0]
	v_pk_fma_f32 v[94:95], v[110:111], v[94:95], v[126:127]
	v_pk_fma_f32 v[96:97], v[112:113], v[96:97], v[128:129]
	v_cvt_pk_bf16_f32 v84, v94, v95
	v_cvt_pk_bf16_f32 v85, v96, v97
	global_store_dwordx2 v9, v[84:85], s[58:59] offset:512
	s_waitcnt vmcnt(17)
	v_pk_add_f32 v[98:99], v[98:99], 1.0 op_sel_hi:[1,0]
	v_pk_add_f32 v[100:101], v[100:101], 1.0 op_sel_hi:[1,0]
	v_pk_fma_f32 v[98:99], v[114:115], v[98:99], v[130:131]
	v_pk_fma_f32 v[100:101], v[116:117], v[100:101], v[132:133]
	v_cvt_pk_bf16_f32 v82, v98, v99
	v_cvt_pk_bf16_f32 v83, v100, v101
	global_store_dwordx2 v9, v[82:83], s[58:59] offset:1024
	s_waitcnt vmcnt(15)
	v_pk_add_f32 v[102:103], v[102:103], 1.0 op_sel_hi:[1,0]
	v_pk_add_f32 v[104:105], v[104:105], 1.0 op_sel_hi:[1,0]
	v_pk_fma_f32 v[102:103], v[118:119], v[102:103], v[134:135]
	v_pk_fma_f32 v[104:105], v[120:121], v[104:105], v[136:137]
	v_cvt_pk_bf16_f32 v84, v102, v103
	v_cvt_pk_bf16_f32 v85, v104, v105
	global_store_dwordx2 v9, v[84:85], s[58:59] offset:1536
	s_add_u32 s58, s58, 0x400000
	s_addc_u32 s59, s59, 0
	s_add_u32 s48, s44, s41
	s_addc_u32 s49, s45, 0
	s_add_u32 s50, s46, 0x6000
	s_addc_u32 s51, s47, 0
	s_add_u32 s52, s50, 0x1000
	s_addc_u32 s53, s51, 0
	global_load_dwordx4 v[90:93], v8, s[52:53]
	global_load_dwordx4 v[106:109], v8, s[48:49]
	global_load_dwordx4 v[122:125], v8, s[50:51]
	global_load_dwordx4 v[94:97], v8, s[52:53] offset:1024
	global_load_dwordx4 v[110:113], v8, s[48:49] offset:1024
	global_load_dwordx4 v[126:129], v8, s[50:51] offset:1024
	global_load_dwordx4 v[98:101], v8, s[52:53] offset:2048
	global_load_dwordx4 v[114:117], v8, s[48:49] offset:2048
	global_load_dwordx4 v[130:133], v8, s[50:51] offset:2048
	global_load_dwordx4 v[102:105], v8, s[52:53] offset:3072
	global_load_dwordx4 v[118:121], v8, s[48:49] offset:3072
	global_load_dwordx4 v[134:137], v8, s[50:51] offset:3072
	s_waitcnt vmcnt(25)
	v_pk_add_f32 v[18:19], v[18:19], 1.0 op_sel_hi:[1,0]
	v_pk_add_f32 v[20:21], v[20:21], 1.0 op_sel_hi:[1,0]
	v_pk_fma_f32 v[18:19], v[50:51], v[18:19], v[66:67]
	v_pk_fma_f32 v[20:21], v[52:53], v[20:21], v[68:69]
	v_cvt_pk_bf16_f32 v82, v18, v19
	v_cvt_pk_bf16_f32 v83, v20, v21
	global_store_dwordx2 v9, v[82:83], s[58:59]
	s_waitcnt vmcnt(23)
	v_pk_add_f32 v[22:23], v[22:23], 1.0 op_sel_hi:[1,0]
	v_pk_add_f32 v[24:25], v[24:25], 1.0 op_sel_hi:[1,0]
	v_pk_fma_f32 v[22:23], v[54:55], v[22:23], v[70:71]
	v_pk_fma_f32 v[24:25], v[56:57], v[24:25], v[72:73]
	v_cvt_pk_bf16_f32 v84, v22, v23
	v_cvt_pk_bf16_f32 v85, v24, v25
	global_store_dwordx2 v9, v[84:85], s[58:59] offset:512
	s_waitcnt vmcnt(21)
	v_pk_add_f32 v[26:27], v[26:27], 1.0 op_sel_hi:[1,0]
	v_pk_add_f32 v[28:29], v[28:29], 1.0 op_sel_hi:[1,0]
	v_pk_fma_f32 v[26:27], v[58:59], v[26:27], v[74:75]
	v_pk_fma_f32 v[28:29], v[60:61], v[28:29], v[76:77]
	v_cvt_pk_bf16_f32 v82, v26, v27
	v_cvt_pk_bf16_f32 v83, v28, v29
	global_store_dwordx2 v9, v[82:83], s[58:59] offset:1024
	s_waitcnt vmcnt(19)
	v_pk_add_f32 v[30:31], v[30:31], 1.0 op_sel_hi:[1,0]
	v_pk_add_f32 v[32:33], v[32:33], 1.0 op_sel_hi:[1,0]
	v_pk_fma_f32 v[30:31], v[62:63], v[30:31], v[78:79]
	v_pk_fma_f32 v[32:33], v[64:65], v[32:33], v[80:81]
	v_cvt_pk_bf16_f32 v84, v30, v31
	v_cvt_pk_bf16_f32 v85, v32, v33
	global_store_dwordx2 v9, v[84:85], s[58:59] offset:1536
	s_add_u32 s58, s58, 0x400000
	s_addc_u32 s59, s59, 0
	s_add_u32 s48, s44, s41
	s_addc_u32 s49, s45, 0
	s_add_u32 s48, s48, 0x800000
	s_addc_u32 s49, s49, 0
	s_add_u32 s50, s46, 0xc000
	s_addc_u32 s51, s47, 0
	s_add_u32 s52, s50, 0x1000
	s_addc_u32 s53, s51, 0
	global_load_dwordx4 v[18:21], v8, s[52:53]
	global_load_dwordx4 v[50:53], v8, s[48:49]
	global_load_dwordx4 v[66:69], v8, s[50:51]
	global_load_dwordx4 v[22:25], v8, s[52:53] offset:1024
	global_load_dwordx4 v[54:57], v8, s[48:49] offset:1024
	global_load_dwordx4 v[70:73], v8, s[50:51] offset:1024
	global_load_dwordx4 v[26:29], v8, s[52:53] offset:2048
	global_load_dwordx4 v[58:61], v8, s[48:49] offset:2048
	global_load_dwordx4 v[74:77], v8, s[50:51] offset:2048
	global_load_dwordx4 v[30:33], v8, s[52:53] offset:3072
	global_load_dwordx4 v[62:65], v8, s[48:49] offset:3072
	global_load_dwordx4 v[78:81], v8, s[50:51] offset:3072
	s_waitcnt vmcnt(25)
	v_pk_add_f32 v[90:91], v[90:91], 1.0 op_sel_hi:[1,0]
	v_pk_add_f32 v[92:93], v[92:93], 1.0 op_sel_hi:[1,0]
	v_pk_fma_f32 v[90:91], v[106:107], v[90:91], v[122:123]
	v_pk_fma_f32 v[92:93], v[108:109], v[92:93], v[124:125]
	v_cvt_pk_bf16_f32 v82, v90, v91
	v_cvt_pk_bf16_f32 v83, v92, v93
	global_store_dwordx2 v9, v[82:83], s[58:59]
	s_waitcnt vmcnt(23)
	v_pk_add_f32 v[94:95], v[94:95], 1.0 op_sel_hi:[1,0]
	v_pk_add_f32 v[96:97], v[96:97], 1.0 op_sel_hi:[1,0]
	v_pk_fma_f32 v[94:95], v[110:111], v[94:95], v[126:127]
	v_pk_fma_f32 v[96:97], v[112:113], v[96:97], v[128:129]
	v_cvt_pk_bf16_f32 v84, v94, v95
	v_cvt_pk_bf16_f32 v85, v96, v97
	global_store_dwordx2 v9, v[84:85], s[58:59] offset:512
	s_waitcnt vmcnt(21)
	v_pk_add_f32 v[98:99], v[98:99], 1.0 op_sel_hi:[1,0]
	v_pk_add_f32 v[100:101], v[100:101], 1.0 op_sel_hi:[1,0]
	v_pk_fma_f32 v[98:99], v[114:115], v[98:99], v[130:131]
	v_pk_fma_f32 v[100:101], v[116:117], v[100:101], v[132:133]
	v_cvt_pk_bf16_f32 v82, v98, v99
	v_cvt_pk_bf16_f32 v83, v100, v101
	global_store_dwordx2 v9, v[82:83], s[58:59] offset:1024
	s_waitcnt vmcnt(19)
	v_pk_add_f32 v[102:103], v[102:103], 1.0 op_sel_hi:[1,0]
	v_pk_add_f32 v[104:105], v[104:105], 1.0 op_sel_hi:[1,0]
	v_pk_fma_f32 v[102:103], v[118:119], v[102:103], v[134:135]
	v_pk_fma_f32 v[104:105], v[120:121], v[104:105], v[136:137]
	v_cvt_pk_bf16_f32 v84, v102, v103
	v_cvt_pk_bf16_f32 v85, v104, v105
	global_store_dwordx2 v9, v[84:85], s[58:59] offset:1536
	s_add_u32 s58, s58, 0x400000
	s_addc_u32 s59, s59, 0
	s_add_u32 s48, s44, s41
	s_addc_u32 s49, s45, 0
	s_add_u32 s48, s48, 0x1000000
	s_addc_u32 s49, s49, 0
	s_add_u32 s50, s46, 0x12000
	s_addc_u32 s51, s47, 0
	s_add_u32 s52, s50, 0x1000
	s_addc_u32 s53, s51, 0
	global_load_dwordx4 v[90:93], v8, s[52:53]
	global_load_dwordx4 v[106:109], v8, s[48:49]
	global_load_dwordx4 v[122:125], v8, s[50:51]
	global_load_dwordx4 v[94:97], v8, s[52:53] offset:1024
	global_load_dwordx4 v[110:113], v8, s[48:49] offset:1024
	global_load_dwordx4 v[126:129], v8, s[50:51] offset:1024
	global_load_dwordx4 v[98:101], v8, s[52:53] offset:2048
	global_load_dwordx4 v[114:117], v8, s[48:49] offset:2048
	global_load_dwordx4 v[130:133], v8, s[50:51] offset:2048
	global_load_dwordx4 v[102:105], v8, s[52:53] offset:3072
	global_load_dwordx4 v[118:121], v8, s[48:49] offset:3072
	global_load_dwordx4 v[134:137], v8, s[50:51] offset:3072
	s_waitcnt vmcnt(25)
	v_pk_add_f32 v[18:19], v[18:19], 1.0 op_sel_hi:[1,0]
	v_pk_add_f32 v[20:21], v[20:21], 1.0 op_sel_hi:[1,0]
	v_pk_fma_f32 v[18:19], v[50:51], v[18:19], v[66:67]
	v_pk_fma_f32 v[20:21], v[52:53], v[20:21], v[68:69]
	v_cvt_pk_bf16_f32 v82, v18, v19
	v_cvt_pk_bf16_f32 v83, v20, v21
	global_store_dwordx2 v9, v[82:83], s[58:59]
	s_waitcnt vmcnt(23)
	v_pk_add_f32 v[22:23], v[22:23], 1.0 op_sel_hi:[1,0]
	v_pk_add_f32 v[24:25], v[24:25], 1.0 op_sel_hi:[1,0]
	v_pk_fma_f32 v[22:23], v[54:55], v[22:23], v[70:71]
	v_pk_fma_f32 v[24:25], v[56:57], v[24:25], v[72:73]
	v_cvt_pk_bf16_f32 v84, v22, v23
	v_cvt_pk_bf16_f32 v85, v24, v25
	global_store_dwordx2 v9, v[84:85], s[58:59] offset:512
	s_waitcnt vmcnt(21)
	v_pk_add_f32 v[26:27], v[26:27], 1.0 op_sel_hi:[1,0]
	v_pk_add_f32 v[28:29], v[28:29], 1.0 op_sel_hi:[1,0]
	v_pk_fma_f32 v[26:27], v[58:59], v[26:27], v[74:75]
	v_pk_fma_f32 v[28:29], v[60:61], v[28:29], v[76:77]
	v_cvt_pk_bf16_f32 v82, v26, v27
	v_cvt_pk_bf16_f32 v83, v28, v29
	global_store_dwordx2 v9, v[82:83], s[58:59] offset:1024
	s_waitcnt vmcnt(19)
	v_pk_add_f32 v[30:31], v[30:31], 1.0 op_sel_hi:[1,0]
	v_pk_add_f32 v[32:33], v[32:33], 1.0 op_sel_hi:[1,0]
	v_pk_fma_f32 v[30:31], v[62:63], v[30:31], v[78:79]
	v_pk_fma_f32 v[32:33], v[64:65], v[32:33], v[80:81]
	v_cvt_pk_bf16_f32 v84, v30, v31
	v_cvt_pk_bf16_f32 v85, v32, v33
	global_store_dwordx2 v9, v[84:85], s[58:59] offset:1536
	s_add_u32 s58, s58, 0x400000
	s_addc_u32 s59, s59, 0
	s_add_u32 s48, s44, s41
	s_addc_u32 s49, s45, 0
	s_add_u32 s48, s48, 0x1800000
	s_addc_u32 s49, s49, 0
	s_add_u32 s50, s46, 0x18000
	s_addc_u32 s51, s47, 0
	s_add_u32 s52, s50, 0x1000
	s_addc_u32 s53, s51, 0
	global_load_dwordx4 v[18:21], v8, s[52:53]
	global_load_dwordx4 v[50:53], v8, s[48:49]
	global_load_dwordx4 v[66:69], v8, s[50:51]
	global_load_dwordx4 v[22:25], v8, s[52:53] offset:1024
	global_load_dwordx4 v[54:57], v8, s[48:49] offset:1024
	global_load_dwordx4 v[70:73], v8, s[50:51] offset:1024
	global_load_dwordx4 v[26:29], v8, s[52:53] offset:2048
	global_load_dwordx4 v[58:61], v8, s[48:49] offset:2048
	global_load_dwordx4 v[74:77], v8, s[50:51] offset:2048
	global_load_dwordx4 v[30:33], v8, s[52:53] offset:3072
	global_load_dwordx4 v[62:65], v8, s[48:49] offset:3072
	global_load_dwordx4 v[78:81], v8, s[50:51] offset:3072
	s_waitcnt vmcnt(25)
	v_pk_add_f32 v[90:91], v[90:91], 1.0 op_sel_hi:[1,0]
	v_pk_add_f32 v[92:93], v[92:93], 1.0 op_sel_hi:[1,0]
	v_pk_fma_f32 v[90:91], v[106:107], v[90:91], v[122:123]
	v_pk_fma_f32 v[92:93], v[108:109], v[92:93], v[124:125]
	v_cvt_pk_bf16_f32 v82, v90, v91
	v_cvt_pk_bf16_f32 v83, v92, v93
	global_store_dwordx2 v9, v[82:83], s[58:59]
	s_waitcnt vmcnt(23)
	v_pk_add_f32 v[94:95], v[94:95], 1.0 op_sel_hi:[1,0]
	v_pk_add_f32 v[96:97], v[96:97], 1.0 op_sel_hi:[1,0]
	v_pk_fma_f32 v[94:95], v[110:111], v[94:95], v[126:127]
	v_pk_fma_f32 v[96:97], v[112:113], v[96:97], v[128:129]
	v_cvt_pk_bf16_f32 v84, v94, v95
	v_cvt_pk_bf16_f32 v85, v96, v97
	global_store_dwordx2 v9, v[84:85], s[58:59] offset:512
	s_waitcnt vmcnt(21)
	v_pk_add_f32 v[98:99], v[98:99], 1.0 op_sel_hi:[1,0]
	v_pk_add_f32 v[100:101], v[100:101], 1.0 op_sel_hi:[1,0]
	v_pk_fma_f32 v[98:99], v[114:115], v[98:99], v[130:131]
	v_pk_fma_f32 v[100:101], v[116:117], v[100:101], v[132:133]
	v_cvt_pk_bf16_f32 v82, v98, v99
	v_cvt_pk_bf16_f32 v83, v100, v101
	global_store_dwordx2 v9, v[82:83], s[58:59] offset:1024
	s_waitcnt vmcnt(19)
	v_pk_add_f32 v[102:103], v[102:103], 1.0 op_sel_hi:[1,0]
	v_pk_add_f32 v[104:105], v[104:105], 1.0 op_sel_hi:[1,0]
	v_pk_fma_f32 v[102:103], v[118:119], v[102:103], v[134:135]
	v_pk_fma_f32 v[104:105], v[120:121], v[104:105], v[136:137]
	v_cvt_pk_bf16_f32 v84, v102, v103
	v_cvt_pk_bf16_f32 v85, v104, v105
	global_store_dwordx2 v9, v[84:85], s[58:59] offset:1536
	s_add_u32 s58, s58, 0x400000
	s_addc_u32 s59, s59, 0
	s_waitcnt vmcnt(13)
	v_pk_add_f32 v[18:19], v[18:19], 1.0 op_sel_hi:[1,0]
	v_pk_add_f32 v[20:21], v[20:21], 1.0 op_sel_hi:[1,0]
	v_pk_fma_f32 v[18:19], v[50:51], v[18:19], v[66:67]
	v_pk_fma_f32 v[20:21], v[52:53], v[20:21], v[68:69]
	v_cvt_pk_bf16_f32 v82, v18, v19
	v_cvt_pk_bf16_f32 v83, v20, v21
	global_store_dwordx2 v9, v[82:83], s[58:59]
	s_waitcnt vmcnt(11)
	v_pk_add_f32 v[22:23], v[22:23], 1.0 op_sel_hi:[1,0]
	v_pk_add_f32 v[24:25], v[24:25], 1.0 op_sel_hi:[1,0]
	v_pk_fma_f32 v[22:23], v[54:55], v[22:23], v[70:71]
	v_pk_fma_f32 v[24:25], v[56:57], v[24:25], v[72:73]
	v_cvt_pk_bf16_f32 v84, v22, v23
	v_cvt_pk_bf16_f32 v85, v24, v25
	global_store_dwordx2 v9, v[84:85], s[58:59] offset:512
	s_waitcnt vmcnt(9)
	v_pk_add_f32 v[26:27], v[26:27], 1.0 op_sel_hi:[1,0]
	v_pk_add_f32 v[28:29], v[28:29], 1.0 op_sel_hi:[1,0]
	v_pk_fma_f32 v[26:27], v[58:59], v[26:27], v[74:75]
	v_pk_fma_f32 v[28:29], v[60:61], v[28:29], v[76:77]
	v_cvt_pk_bf16_f32 v82, v26, v27
	v_cvt_pk_bf16_f32 v83, v28, v29
	global_store_dwordx2 v9, v[82:83], s[58:59] offset:1024
	s_waitcnt vmcnt(7)
	v_pk_add_f32 v[30:31], v[30:31], 1.0 op_sel_hi:[1,0]
	v_pk_add_f32 v[32:33], v[32:33], 1.0 op_sel_hi:[1,0]
	v_pk_fma_f32 v[30:31], v[62:63], v[30:31], v[78:79]
	v_pk_fma_f32 v[32:33], v[64:65], v[32:33], v[80:81]
	v_cvt_pk_bf16_f32 v84, v30, v31
	v_cvt_pk_bf16_f32 v85, v32, v33
	global_store_dwordx2 v9, v[84:85], s[58:59] offset:1536
